# attention QK: removed compiler vmcnt ladder that waited for next-tile LDS-DMA
# speedup vs baseline: 1.0104x; 1.0104x over previous
.LBB0_268:
	s_waitcnt vmcnt(0) lgkmcnt(0)
	s_barrier
	v_add_u32_e32 v234, s90, v231
	v_add_u32_e32 v0, 0x80000, v234
	s_mov_b32 s4, m0
	s_mov_b32 m0, s71
	s_nop 0
	global_load_lds_dwordx4 v0, s[62:63]
	s_mov_b32 m0, s4
	v_add_u32_e32 v235, s90, v229
	v_add_u32_e32 v0, 0x80000, v235
	s_mov_b32 s4, m0
	s_mov_b32 m0, s92
	s_nop 0
	global_load_lds_dwordx4 v0, s[62:63]
	s_mov_b32 m0, s4
	v_add_u32_e32 v236, s90, v227
	v_add_u32_e32 v0, 0x80000, v236
	s_mov_b32 s4, m0
	s_mov_b32 m0, s70
	s_nop 0
	global_load_lds_dwordx4 v0, s[62:63]
	s_mov_b32 m0, s4
	v_add_u32_e32 v237, s90, v225
	v_add_u32_e32 v0, 0x80000, v237
	s_mov_b32 s4, m0
	s_mov_b32 m0, s80
	s_nop 0
	global_load_lds_dwordx4 v0, s[62:63]
	s_mov_b32 m0, s4
	v_add_u32_e32 v238, s90, v230
	v_add_u32_e32 v0, 0x80000, v238
	s_mov_b32 s4, m0
	s_mov_b32 m0, s81
	s_nop 0
	global_load_lds_dwordx4 v0, s[62:63]
	s_mov_b32 m0, s4
	v_add_u32_e32 v239, s90, v228
	v_add_u32_e32 v0, 0x80000, v239
	s_mov_b32 s4, m0
	s_mov_b32 m0, s50
	s_nop 0
	global_load_lds_dwordx4 v0, s[62:63]
	s_mov_b32 m0, s4
	v_add_u32_e32 v240, s90, v226
	v_add_u32_e32 v0, 0x80000, v240
	s_mov_b32 s4, m0
	s_mov_b32 m0, s51
	s_nop 0
	global_load_lds_dwordx4 v0, s[62:63]
	s_mov_b32 m0, s4
	v_add_u32_e32 v241, s90, v224
	v_add_u32_e32 v0, 0x80000, v241
	s_mov_b32 s4, m0
	s_mov_b32 m0, s94
	s_nop 0
	global_load_lds_dwordx4 v0, s[62:63]
	s_mov_b32 m0, s4
	s_cmp_gt_u32 s58, s89
	s_cbranch_scc1 .LBB0_307
	v_mov_b32_e32 v0, v221
	v_mov_b32_e32 v242, v222
	s_add_i32 s4, s91, 0xb0
	v_add_u32_e32 v134, 0, v0
	ds_read_b128 v[130:133], v134
	v_xad_u32 v166, v0, 32, 0
	ds_read_b128 v[162:165], v166
	s_cmp_le_u32 s4, s3
	s_waitcnt lgkmcnt(1)
	v_mfma_f32_32x32x16_bf16 v[146:161], v[130:133], v[178:181], 0
	ds_read_b128 v[130:133], v134 offset:8192
	s_waitcnt lgkmcnt(1)
	v_mfma_f32_32x32x16_bf16 v[146:161], v[162:165], v[182:185], v[146:161]
	ds_read_b128 v[162:165], v166 offset:8192
	v_xad_u32 v166, v0, 64, 0
	s_waitcnt lgkmcnt(1)
	v_mfma_f32_32x32x16_bf16 v[130:145], v[130:133], v[178:181], 0
	s_waitcnt lgkmcnt(0)
	v_mfma_f32_32x32x16_bf16 v[130:145], v[162:165], v[182:185], v[130:145]
	ds_read_b128 v[162:165], v166
	s_waitcnt lgkmcnt(0)
	v_mfma_f32_32x32x16_bf16 v[146:161], v[162:165], v[186:189], v[146:161]
	ds_read_b128 v[162:165], v166 offset:8192
	s_waitcnt lgkmcnt(0)
	v_mfma_f32_32x32x16_bf16 v[130:145], v[162:165], v[186:189], v[130:145]
	v_xor_b32_e32 v162, 0x60, v0
	v_add_u32_e32 v166, 0, v162
	ds_read_b128 v[162:165], v166
	s_waitcnt lgkmcnt(0)
	v_mfma_f32_32x32x16_bf16 v[146:161], v[162:165], v[190:193], v[146:161]
	ds_read_b128 v[162:165], v166 offset:8192
	s_waitcnt lgkmcnt(0)
	v_mfma_f32_32x32x16_bf16 v[130:145], v[162:165], v[190:193], v[130:145]
	v_xor_b32_e32 v162, 0x80, v0
	v_add_u32_e32 v166, 0, v162
	ds_read_b128 v[162:165], v166
	s_waitcnt lgkmcnt(0)
	v_mfma_f32_32x32x16_bf16 v[146:161], v[162:165], v[194:197], v[146:161]
	ds_read_b128 v[162:165], v166 offset:8192
	s_waitcnt lgkmcnt(0)
	v_mfma_f32_32x32x16_bf16 v[130:145], v[162:165], v[194:197], v[130:145]
	v_xor_b32_e32 v162, 0xa0, v0
	v_add_u32_e32 v166, 0, v162
	ds_read_b128 v[162:165], v166
	s_waitcnt lgkmcnt(0)
	v_mfma_f32_32x32x16_bf16 v[146:161], v[162:165], v[198:201], v[146:161]
	ds_read_b128 v[162:165], v166 offset:8192
	s_waitcnt lgkmcnt(0)
	v_mfma_f32_32x32x16_bf16 v[130:145], v[162:165], v[198:201], v[130:145]
	v_xor_b32_e32 v162, 0xc0, v0
	v_add_u32_e32 v166, 0, v162
	ds_read_b128 v[162:165], v166
	v_xor_b32_e32 v0, 0xe0, v0
	v_add_u32_e32 v0, 0, v0
	s_waitcnt lgkmcnt(0)
	v_mfma_f32_32x32x16_bf16 v[146:161], v[162:165], v[202:205], v[146:161]
	ds_read_b128 v[162:165], v166 offset:8192
	s_waitcnt lgkmcnt(0)
	v_mfma_f32_32x32x16_bf16 v[130:145], v[162:165], v[202:205], v[130:145]
	ds_read_b128 v[162:165], v0
	s_waitcnt lgkmcnt(0)
	v_mfma_f32_32x32x16_bf16 v[146:161], v[162:165], v[206:209], v[146:161]
	ds_read_b128 v[162:165], v0 offset:8192
	s_waitcnt lgkmcnt(0)
	v_mfma_f32_32x32x16_bf16 v[130:145], v[162:165], v[206:209], v[130:145]
	s_cbranch_scc1 .LBB0_303
	v_add_u32_e32 v164, 0x5b, v223
	v_min_u32_e32 v0, 0x9f, v164
	v_subrev_u32_e32 v0, 32, v0
	v_cmp_gt_i32_e32 vcc, 32, v164
	v_cmp_lt_i32_e64 s[4:5], -1, v164
	v_mov_b32_e32 v163, 0xff800000
	v_cndmask_b32_e64 v0, v0, 0, vcc
	v_lshl_add_u32 v0, v0, 2, 0
	v_add_u32_e32 v0, 0x20000, v0
	ds_read_b32 v0, v0
	v_mov_b32_e32 v162, 0xff800000
	s_and_saveexec_b64 s[6:7], s[4:5]
	s_cbranch_execz .LBB0_272
	v_min_u32_e32 v162, 0x7f, v164
	v_lshl_add_u32 v162, v162, 2, 0
	v_add_u32_e32 v162, 0x20000, v162
	ds_read_b32 v162, v162
	s_waitcnt lgkmcnt(0)
	v_add_f32_e32 v162, v146, v162

.LBB0_312:
	s_cmp_ge_u32 s58, s89
	s_cbranch_scc1 .LBB0_266
	v_mov_b32_e32 v234, v222
	v_mov_b32_e32 v166, v221
	s_cmp_le_i32 s91, s73
	v_add_u32_e32 v134, 0, v166
	v_add_u32_e32 v130, 0x10000, v134
	ds_read_b128 v[130:133], v130
	v_xad_u32 v167, v166, 32, 0
	v_add_u32_e32 v162, 0x10000, v167
	v_add_u32_e32 v134, 0x12000, v134
	ds_read_b128 v[162:165], v162
	v_add_u32_e32 v167, 0x12000, v167
	s_waitcnt lgkmcnt(1)
	v_mfma_f32_32x32x16_bf16 v[146:161], v[130:133], v[178:181], 0
	ds_read_b128 v[130:133], v134
	s_waitcnt lgkmcnt(1)
	v_mfma_f32_32x32x16_bf16 v[146:161], v[162:165], v[182:185], v[146:161]
	ds_read_b128 v[162:165], v167
	v_xad_u32 v167, v166, 64, 0
	s_waitcnt lgkmcnt(1)
	v_mfma_f32_32x32x16_bf16 v[130:145], v[130:133], v[178:181], 0
	s_waitcnt lgkmcnt(0)
	v_mfma_f32_32x32x16_bf16 v[130:145], v[162:165], v[182:185], v[130:145]
	v_add_u32_e32 v162, 0x10000, v167
	ds_read_b128 v[162:165], v162
	v_add_u32_e32 v167, 0x12000, v167
	s_waitcnt lgkmcnt(0)
	v_mfma_f32_32x32x16_bf16 v[146:161], v[162:165], v[186:189], v[146:161]
	ds_read_b128 v[162:165], v167
	s_waitcnt lgkmcnt(0)
	v_mfma_f32_32x32x16_bf16 v[130:145], v[162:165], v[186:189], v[130:145]
	v_xor_b32_e32 v162, 0x60, v166
	v_add_u32_e32 v167, 0, v162
	v_add_u32_e32 v162, 0x10000, v167
	ds_read_b128 v[162:165], v162
	v_add_u32_e32 v167, 0x12000, v167
	s_waitcnt lgkmcnt(0)
	v_mfma_f32_32x32x16_bf16 v[146:161], v[162:165], v[190:193], v[146:161]
	ds_read_b128 v[162:165], v167
	s_waitcnt lgkmcnt(0)
	v_mfma_f32_32x32x16_bf16 v[130:145], v[162:165], v[190:193], v[130:145]
	v_xor_b32_e32 v162, 0x80, v166
	v_add_u32_e32 v167, 0, v162
	v_add_u32_e32 v162, 0x10000, v167
	ds_read_b128 v[162:165], v162
	v_add_u32_e32 v167, 0x12000, v167
	s_waitcnt lgkmcnt(0)
	v_mfma_f32_32x32x16_bf16 v[146:161], v[162:165], v[194:197], v[146:161]
	ds_read_b128 v[162:165], v167
	s_waitcnt lgkmcnt(0)
	v_mfma_f32_32x32x16_bf16 v[130:145], v[162:165], v[194:197], v[130:145]
	v_xor_b32_e32 v162, 0xa0, v166
	v_add_u32_e32 v167, 0, v162
	v_add_u32_e32 v162, 0x10000, v167
	ds_read_b128 v[162:165], v162
	v_add_u32_e32 v167, 0x12000, v167
	s_waitcnt lgkmcnt(0)
	v_mfma_f32_32x32x16_bf16 v[146:161], v[162:165], v[198:201], v[146:161]
	ds_read_b128 v[162:165], v167
	s_waitcnt lgkmcnt(0)
	v_mfma_f32_32x32x16_bf16 v[130:145], v[162:165], v[198:201], v[130:145]
	v_xor_b32_e32 v162, 0xc0, v166
	v_add_u32_e32 v167, 0, v162
	v_add_u32_e32 v162, 0x10000, v167
	ds_read_b128 v[162:165], v162
	v_add_u32_e32 v167, 0x12000, v167
	s_waitcnt lgkmcnt(0)
	v_mfma_f32_32x32x16_bf16 v[146:161], v[162:165], v[202:205], v[146:161]
	ds_read_b128 v[162:165], v167
	s_waitcnt lgkmcnt(0)
	v_mfma_f32_32x32x16_bf16 v[130:145], v[162:165], v[202:205], v[130:145]
	v_xor_b32_e32 v162, 0xe0, v166
	v_add_u32_e32 v166, 0, v162
	v_add_u32_e32 v162, 0x10000, v166
	ds_read_b128 v[162:165], v162
	v_add_u32_e32 v166, 0x12000, v166
	s_waitcnt lgkmcnt(0)
	v_mfma_f32_32x32x16_bf16 v[146:161], v[162:165], v[206:209], v[146:161]
	ds_read_b128 v[162:165], v166
	s_waitcnt lgkmcnt(0)
	v_mfma_f32_32x32x16_bf16 v[130:145], v[162:165], v[206:209], v[130:145]
	s_cbranch_scc1 .LBB0_347
	v_add_u32_e32 v164, 27, v223
	v_min_u32_e32 v162, 0x9f, v164
	v_subrev_u32_e32 v162, 32, v162
	v_cmp_gt_i32_e32 vcc, 32, v164
	v_cmp_lt_i32_e64 s[4:5], -1, v164
	v_mov_b32_e32 v163, 0xff800000
	v_cndmask_b32_e64 v162, v162, 0, vcc
	v_lshl_add_u32 v162, v162, 2, 0
	v_add_u32_e32 v162, 0x20000, v162
	ds_read_b32 v233, v162
	v_mov_b32_e32 v162, 0xff800000
	s_and_saveexec_b64 s[6:7], s[4:5]
	s_cbranch_execz .LBB0_316
	v_min_u32_e32 v162, 0x7f, v164
	v_lshl_add_u32 v162, v162, 2, 0
	v_add_u32_e32 v162, 0x20000, v162
	ds_read_b32 v162, v162
	s_waitcnt lgkmcnt(0)
	v_add_f32_e32 v162, v146, v162
